# stacked: out_rows merge + mem_attn staging de-serialised + prep S1 q-batch butterflies merged + MLA qs1 wave-uniform test shortened to v_cmp/s_or/s_cbranch
# speedup vs baseline: 1.0019x; 1.0019x over previous
.LBB0_1388:
	v_max3_f32 v239, v96, s27, v97
	v_max3_f32 v239, v239, v98, v99
	v_max3_f32 v239, v239, v100, v101
	v_max3_f32 v239, v239, v102, v103
	v_max3_f32 v239, v239, v128, v129
	v_max3_f32 v239, v239, v130, v131
	v_max3_f32 v239, v239, v140, v141
	v_max3_f32 v239, v239, v142, v143
	v_mov_b32_e32 v237, v239
	s_nop 1
	v_permlane16_swap_b32_e32 v237, v239
	v_max_f32_e32 v237, v239, v237
	v_mov_b32_e32 v238, v237
	s_nop 1
	v_permlane32_swap_b32_e32 v238, v237
	v_max_f32_e32 v237, v237, v238
	v_cmp_lt_f32_e32 vcc, s7, v237
	s_or_b64 vcc, s[38:39], vcc
	s_cbranch_vccz .LBB0_1390
	v_max_f32_e32 v238, v237, v237
	v_max_f32_e32 v238, 0, v238
	v_cndmask_b32_e64 v237, v238, v237, s[38:39]
	v_exp_f32_e64 v238, -v237
	v_add_f32_e32 v233, v233, v237
	v_sub_f32_e32 v96, v96, v237
	v_sub_f32_e32 v97, v97, v237
	v_mul_f32_e32 v193, v193, v238
	v_sub_f32_e32 v98, v98, v237
	v_sub_f32_e32 v99, v99, v237
	v_sub_f32_e32 v100, v100, v237
	v_sub_f32_e32 v101, v101, v237
	v_sub_f32_e32 v102, v102, v237
	v_sub_f32_e32 v103, v103, v237
	v_sub_f32_e32 v128, v128, v237
	v_sub_f32_e32 v129, v129, v237
	v_sub_f32_e32 v130, v130, v237
	v_sub_f32_e32 v131, v131, v237
	v_sub_f32_e32 v140, v140, v237
	v_sub_f32_e32 v141, v141, v237
	v_sub_f32_e32 v142, v142, v237
	v_sub_f32_e32 v143, v143, v237
	v_pk_mul_f32 v[30:31], v[30:31], v[238:239] op_sel_hi:[1,0]
	v_pk_mul_f32 v[28:29], v[28:29], v[238:239] op_sel_hi:[1,0]
	v_pk_mul_f32 v[26:27], v[26:27], v[238:239] op_sel_hi:[1,0]
	v_pk_mul_f32 v[24:25], v[24:25], v[238:239] op_sel_hi:[1,0]
	v_pk_mul_f32 v[22:23], v[22:23], v[238:239] op_sel_hi:[1,0]
	v_pk_mul_f32 v[20:21], v[20:21], v[238:239] op_sel_hi:[1,0]
	v_pk_mul_f32 v[18:19], v[18:19], v[238:239] op_sel_hi:[1,0]
	v_pk_mul_f32 v[16:17], v[16:17], v[238:239] op_sel_hi:[1,0]
	v_pk_mul_f32 v[14:15], v[14:15], v[238:239] op_sel_hi:[1,0]
	v_pk_mul_f32 v[12:13], v[12:13], v[238:239] op_sel_hi:[1,0]
	v_pk_mul_f32 v[10:11], v[10:11], v[238:239] op_sel_hi:[1,0]
	v_pk_mul_f32 v[8:9], v[8:9], v[238:239] op_sel_hi:[1,0]
	v_pk_mul_f32 v[6:7], v[6:7], v[238:239] op_sel_hi:[1,0]
	v_pk_mul_f32 v[4:5], v[4:5], v[238:239] op_sel_hi:[1,0]
	v_pk_mul_f32 v[2:3], v[2:3], v[238:239] op_sel_hi:[1,0]
	v_pk_mul_f32 v[0:1], v[0:1], v[238:239] op_sel_hi:[1,0]
